# prologue: nt hint on once-read f32 weight and x loads
# speedup vs baseline: 1.0072x; 1.0072x over previous
; #define GAS __attribute__((address_space(1)))
; #define LAS __attribute__((address_space(3)))
; #define LDS_WAIT() asm volatile("s_waitcnt lgkmcnt(0)" ::: "memory")
; __device__ __forceinline__ unsigned pk2(float lo, float hi) { return pg8::cvt_pk_bf16(lo, hi); }
; __device__ __forceinline__ void p0_transpose_item(const float* W, int K, int N, bf16r* WT, LAS float* scr, int item, int lane) {
;     const int nblk = N / 64, kb = item / nblk, nb = item % nblk, k0 = 64 * kb, n0 = 64 * nb;
; #pragma unroll 8
;     for (int i = 0; i < 32; ++i) { const int kk = 2 * i + (lane >> 5); const f32x2 v = *(const f32x2*)(W + (size_t)(k0 + kk) * N + n0 + 2 * (lane & 31)); scr[kk * 65 + 2 * (lane & 31)] = v.x; scr[kk * 65 + 2 * (lane & 31) + 1] = v.y; }
;     LDS_WAIT(); asm volatile("" ::: "memory");
;     const int c = lane & 7;
; #pragma unroll
;     for (int j = 0; j < 8; ++j) { const int n = (lane >> 3) + 8 * j; const LAS float* s = scr + (8 * c) * 65 + n;
;         v4u o; o.x = pk2(s[0 * 65], s[1 * 65]); o.y = pk2(s[2 * 65], s[3 * 65]); o.z = pk2(s[4 * 65], s[5 * 65]); o.w = pk2(s[6 * 65], s[7 * 65]);
;         *(GAS v4u*)(WT + (size_t)(n0 + n) * K + k0 + 8 * c) = o; }
;     LDS_WAIT(); asm volatile("" ::: "memory");
; }
.LBB0_20:
	v_lshl_add_u64 v[56:57], v[34:35], 0, s[4:5]
	v_lshl_add_u64 v[58:59], v[32:33], 0, s[4:5]
	v_lshl_add_u64 v[60:61], v[30:31], 0, s[4:5]
	v_lshl_add_u64 v[62:63], v[28:29], 0, s[4:5]
	v_lshl_add_u64 v[64:65], v[26:27], 0, s[4:5]
	v_lshl_add_u64 v[66:67], v[24:25], 0, s[4:5]
	v_lshl_add_u64 v[68:69], v[22:23], 0, s[4:5]
	v_lshl_add_u64 v[70:71], v[20:21], 0, s[4:5]
	global_load_dwordx2 v[72:73], v[56:57], off nt
	global_load_dwordx2 v[74:75], v[58:59], off nt
	global_load_dwordx2 v[76:77], v[60:61], off nt
	global_load_dwordx2 v[78:79], v[62:63], off nt
	global_load_dwordx2 v[80:81], v[64:65], off nt
	global_load_dwordx2 v[82:83], v[66:67], off nt
	global_load_dwordx2 v[84:85], v[68:69], off nt
	global_load_dwordx2 v[86:87], v[70:71], off nt
	s_add_u32 s4, s4, 0x40000
	s_addc_u32 s5, s5, 0
	v_add_u32_e32 v55, 0x410, v2
	v_add_u32_e32 v56, 0x618, v2
	v_add_u32_e32 v57, 0x820, v2
	v_add_u32_e32 v58, 0xa28, v2
	v_add_u32_e32 v59, 0xc30, v2
	v_add_u32_e32 v60, 0xe38, v2
	s_cmp_lg_u32 s4, 0x100000
	s_waitcnt vmcnt(7)
	ds_write2_b32 v2, v72, v73 offset1:1
	s_waitcnt vmcnt(6)
	ds_write2_b32 v2, v74, v75 offset0:130 offset1:131
	s_waitcnt vmcnt(5)
	ds_write2_b32 v55, v76, v77 offset1:1
	s_waitcnt vmcnt(4)
	ds_write2_b32 v56, v78, v79 offset1:1
	s_waitcnt vmcnt(3)
	ds_write2_b32 v57, v80, v81 offset1:1
	s_waitcnt vmcnt(2)
	ds_write2_b32 v58, v82, v83 offset1:1
	s_waitcnt vmcnt(1)
	ds_write2_b32 v59, v84, v85 offset1:1
	s_waitcnt vmcnt(0)
	ds_write2_b32 v60, v86, v87 offset1:1
	v_add_u32_e32 v2, 0x1040, v2
	s_cbranch_scc1 .LBB0_20
	s_waitcnt lgkmcnt(0)
	s_lshl_b32 s4, s39, 6
	ds_read2_b32 v[20:21], v37 offset1:65
	s_and_b32 s4, s4, 0xfc0
	s_waitcnt lgkmcnt(0)
	v_cvt_pk_bf16_f32 v20, v20, v21
	ds_read2_b32 v[22:23], v37 offset0:130 offset1:195
	s_lshl_b32 s2, s2, 1
	v_or_b32_e32 v2, s4, v36
	s_waitcnt lgkmcnt(0)
	v_cvt_pk_bf16_f32 v21, v22, v23
	ds_read2_b32 v[22:23], v54 offset0:4 offset1:69
	v_lshl_add_u64 v[26:27], v[6:7], 0, s[2:3]
	v_lshlrev_b32_e32 v2, 13, v2
	s_waitcnt lgkmcnt(0)
	v_cvt_pk_bf16_f32 v22, v22, v23
	ds_read2_b32 v[24:25], v54 offset0:134 offset1:199
	s_waitcnt lgkmcnt(0)
	v_cvt_pk_bf16_f32 v23, v24, v25
	v_lshl_add_u64 v[28:29], v[26:27], 0, v[2:3]
	ds_read2_b32 v[24:25], v37 offset0:8 offset1:73
	global_store_dwordx4 v[28:29], v[20:23], off
	v_or_b32_e32 v2, s4, v38
	v_lshlrev_b32_e32 v2, 13, v2
	s_waitcnt lgkmcnt(0)
	v_cvt_pk_bf16_f32 v20, v24, v25
	ds_read2_b32 v[22:23], v37 offset0:138 offset1:203
	s_waitcnt lgkmcnt(0)
	v_cvt_pk_bf16_f32 v21, v22, v23
	ds_read2_b32 v[22:23], v54 offset0:12 offset1:77
	s_waitcnt lgkmcnt(0)
	v_cvt_pk_bf16_f32 v22, v22, v23
	ds_read2_b32 v[24:25], v54 offset0:142 offset1:207
	s_waitcnt lgkmcnt(0)
	v_cvt_pk_bf16_f32 v23, v24, v25
	v_lshl_add_u64 v[28:29], v[26:27], 0, v[2:3]
	ds_read2_b32 v[24:25], v37 offset0:16 offset1:81
	global_store_dwordx4 v[28:29], v[20:23], off
	v_or_b32_e32 v2, s4, v39
	v_lshlrev_b32_e32 v2, 13, v2
	s_waitcnt lgkmcnt(0)
	v_cvt_pk_bf16_f32 v20, v24, v25
	ds_read2_b32 v[22:23], v37 offset0:146 offset1:211
	s_waitcnt lgkmcnt(0)
	v_cvt_pk_bf16_f32 v21, v22, v23
	ds_read2_b32 v[22:23], v54 offset0:20 offset1:85
	s_waitcnt lgkmcnt(0)
	v_cvt_pk_bf16_f32 v22, v22, v23
	ds_read2_b32 v[24:25], v54 offset0:150 offset1:215
	s_waitcnt lgkmcnt(0)
	v_cvt_pk_bf16_f32 v23, v24, v25
	v_lshl_add_u64 v[28:29], v[26:27], 0, v[2:3]
	ds_read2_b32 v[24:25], v37 offset0:24 offset1:89
	global_store_dwordx4 v[28:29], v[20:23], off
	v_or_b32_e32 v2, s4, v40
	v_lshlrev_b32_e32 v2, 13, v2
	s_waitcnt lgkmcnt(0)
	v_cvt_pk_bf16_f32 v20, v24, v25
	ds_read2_b32 v[22:23], v37 offset0:154 offset1:219
	s_waitcnt lgkmcnt(0)
	v_cvt_pk_bf16_f32 v21, v22, v23
	ds_read2_b32 v[22:23], v54 offset0:28 offset1:93
	s_waitcnt lgkmcnt(0)
	v_cvt_pk_bf16_f32 v22, v22, v23
	ds_read2_b32 v[24:25], v54 offset0:158 offset1:223
	s_waitcnt lgkmcnt(0)
	v_cvt_pk_bf16_f32 v23, v24, v25
	v_lshl_add_u64 v[28:29], v[26:27], 0, v[2:3]
	ds_read2_b32 v[24:25], v37 offset0:32 offset1:97
	global_store_dwordx4 v[28:29], v[20:23], off
	v_or_b32_e32 v2, s4, v41
	v_lshlrev_b32_e32 v2, 13, v2
	s_waitcnt lgkmcnt(0)
	v_cvt_pk_bf16_f32 v20, v24, v25
	ds_read2_b32 v[22:23], v37 offset0:162 offset1:227
	s_waitcnt lgkmcnt(0)
	v_cvt_pk_bf16_f32 v21, v22, v23
	ds_read2_b32 v[22:23], v54 offset0:36 offset1:101
	s_waitcnt lgkmcnt(0)
	v_cvt_pk_bf16_f32 v22, v22, v23
	ds_read2_b32 v[24:25], v54 offset0:166 offset1:231
	s_waitcnt lgkmcnt(0)
	v_cvt_pk_bf16_f32 v23, v24, v25
	v_lshl_add_u64 v[28:29], v[26:27], 0, v[2:3]
	ds_read2_b32 v[24:25], v37 offset0:40 offset1:105
	global_store_dwordx4 v[28:29], v[20:23], off
	v_or_b32_e32 v2, s4, v42
	v_lshlrev_b32_e32 v2, 13, v2
	s_waitcnt lgkmcnt(0)
	v_cvt_pk_bf16_f32 v20, v24, v25
	ds_read2_b32 v[22:23], v37 offset0:170 offset1:235
	s_waitcnt lgkmcnt(0)
	v_cvt_pk_bf16_f32 v21, v22, v23
	ds_read2_b32 v[22:23], v54 offset0:44 offset1:109
	s_waitcnt lgkmcnt(0)
	v_cvt_pk_bf16_f32 v22, v22, v23
	ds_read2_b32 v[24:25], v54 offset0:174 offset1:239
	s_waitcnt lgkmcnt(0)
	v_cvt_pk_bf16_f32 v23, v24, v25
	v_lshl_add_u64 v[28:29], v[26:27], 0, v[2:3]
	ds_read2_b32 v[24:25], v37 offset0:48 offset1:113
	global_store_dwordx4 v[28:29], v[20:23], off
	v_or_b32_e32 v2, s4, v43
	v_lshlrev_b32_e32 v2, 13, v2
	s_waitcnt lgkmcnt(0)
	v_cvt_pk_bf16_f32 v20, v24, v25
	ds_read2_b32 v[22:23], v37 offset0:178 offset1:243
	s_waitcnt lgkmcnt(0)
	v_cvt_pk_bf16_f32 v21, v22, v23
	ds_read2_b32 v[22:23], v54 offset0:52 offset1:117
	s_waitcnt lgkmcnt(0)
	v_cvt_pk_bf16_f32 v22, v22, v23
	ds_read2_b32 v[24:25], v54 offset0:182 offset1:247
	s_waitcnt lgkmcnt(0)
	v_cvt_pk_bf16_f32 v23, v24, v25
	v_lshl_add_u64 v[28:29], v[26:27], 0, v[2:3]
	ds_read2_b32 v[24:25], v37 offset0:56 offset1:121
	global_store_dwordx4 v[28:29], v[20:23], off
	v_or_b32_e32 v2, s4, v44
	v_lshlrev_b32_e32 v2, 13, v2
	s_waitcnt lgkmcnt(0)
	v_cvt_pk_bf16_f32 v20, v24, v25
	ds_read2_b32 v[22:23], v37 offset0:186 offset1:251
	s_waitcnt lgkmcnt(0)
	v_cvt_pk_bf16_f32 v21, v22, v23
	ds_read2_b32 v[22:23], v54 offset0:60 offset1:125
	s_waitcnt lgkmcnt(0)
	v_cvt_pk_bf16_f32 v22, v22, v23
	ds_read2_b32 v[24:25], v54 offset0:190 offset1:255
	s_waitcnt lgkmcnt(0)
	v_cvt_pk_bf16_f32 v23, v24, v25
	v_lshl_add_u64 v[24:25], v[26:27], 0, v[2:3]
	global_store_dwordx4 v[24:25], v[20:23], off
	s_waitcnt lgkmcnt(0)
	s_mov_b64 s[4:5], 0

; #define GAS __attribute__((address_space(1)))
; #define LAS __attribute__((address_space(3)))
; #define LDS_WAIT() asm volatile("s_waitcnt lgkmcnt(0)" ::: "memory")
; __device__ __forceinline__ unsigned pk2(float lo, float hi) { return pg8::cvt_pk_bf16(lo, hi); }
; __device__ __forceinline__ void p0_transpose_item(const float* W, int K, int N, bf16r* WT, LAS float* scr, int item, int lane) {
;     const int nblk = N / 64, kb = item / nblk, nb = item % nblk, k0 = 64 * kb, n0 = 64 * nb;
; #pragma unroll 8
;     for (int i = 0; i < 32; ++i) { const int kk = 2 * i + (lane >> 5); const f32x2 v = *(const f32x2*)(W + (size_t)(k0 + kk) * N + n0 + 2 * (lane & 31)); scr[kk * 65 + 2 * (lane & 31)] = v.x; scr[kk * 65 + 2 * (lane & 31) + 1] = v.y; }
;     LDS_WAIT(); asm volatile("" ::: "memory");
;     const int c = lane & 7;
; #pragma unroll
;     for (int j = 0; j < 8; ++j) { const int n = (lane >> 3) + 8 * j; const LAS float* s = scr + (8 * c) * 65 + n;
;         v4u o; o.x = pk2(s[0 * 65], s[1 * 65]); o.y = pk2(s[2 * 65], s[3 * 65]); o.z = pk2(s[4 * 65], s[5 * 65]); o.w = pk2(s[6 * 65], s[7 * 65]);
;         *(GAS v4u*)(WT + (size_t)(n0 + n) * K + k0 + 8 * c) = o; }
;     LDS_WAIT(); asm volatile("" ::: "memory");
; }
.LBB0_24:
	v_lshl_add_u64 v[56:57], v[34:35], 0, s[4:5]
	v_lshl_add_u64 v[58:59], v[32:33], 0, s[4:5]
	v_lshl_add_u64 v[60:61], v[30:31], 0, s[4:5]
	v_lshl_add_u64 v[62:63], v[28:29], 0, s[4:5]
	v_lshl_add_u64 v[64:65], v[26:27], 0, s[4:5]
	v_lshl_add_u64 v[66:67], v[24:25], 0, s[4:5]
	v_lshl_add_u64 v[68:69], v[22:23], 0, s[4:5]
	v_lshl_add_u64 v[70:71], v[20:21], 0, s[4:5]
	global_load_dwordx2 v[72:73], v[56:57], off nt
	global_load_dwordx2 v[74:75], v[58:59], off nt
	global_load_dwordx2 v[76:77], v[60:61], off nt
	global_load_dwordx2 v[78:79], v[62:63], off nt
	global_load_dwordx2 v[80:81], v[64:65], off nt
	global_load_dwordx2 v[82:83], v[66:67], off nt
	global_load_dwordx2 v[84:85], v[68:69], off nt
	global_load_dwordx2 v[86:87], v[70:71], off nt
	s_add_u32 s4, s4, 0xe0000
	s_addc_u32 s5, s5, 0
	v_add_u32_e32 v55, 0x410, v2
	v_add_u32_e32 v56, 0x618, v2
	v_add_u32_e32 v57, 0x820, v2
	v_add_u32_e32 v58, 0xa28, v2
	v_add_u32_e32 v59, 0xc30, v2
	v_add_u32_e32 v60, 0xe38, v2
	s_cmp_lg_u32 s4, 0x380000
	s_waitcnt vmcnt(7)
	ds_write2_b32 v2, v72, v73 offset1:1
	s_waitcnt vmcnt(6)
	ds_write2_b32 v2, v74, v75 offset0:130 offset1:131
	s_waitcnt vmcnt(5)
	ds_write2_b32 v55, v76, v77 offset1:1
	s_waitcnt vmcnt(4)
	ds_write2_b32 v56, v78, v79 offset1:1
	s_waitcnt vmcnt(3)
	ds_write2_b32 v57, v80, v81 offset1:1
	s_waitcnt vmcnt(2)
	ds_write2_b32 v58, v82, v83 offset1:1
	s_waitcnt vmcnt(1)
	ds_write2_b32 v59, v84, v85 offset1:1
	s_waitcnt vmcnt(0)
	ds_write2_b32 v60, v86, v87 offset1:1
	v_add_u32_e32 v2, 0x1040, v2
	s_cbranch_scc1 .LBB0_24
	s_waitcnt lgkmcnt(0)
	ds_read2_b32 v[20:21], v37 offset1:65
	s_and_b32 s4, 0xffff, s18
	s_and_b32 s2, 0xffff, s7
	s_waitcnt lgkmcnt(0)
	v_cvt_pk_bf16_f32 v20, v20, v21
	ds_read2_b32 v[22:23], v37 offset0:130 offset1:195
	s_lshl_b32 s2, s2, 1
	v_or_b32_e32 v2, s4, v36
	s_waitcnt lgkmcnt(0)
	v_cvt_pk_bf16_f32 v21, v22, v23
	ds_read2_b32 v[22:23], v54 offset0:4 offset1:69
	v_lshl_add_u64 v[26:27], v[8:9], 0, s[2:3]
	v_lshlrev_b32_e32 v2, 13, v2
	s_waitcnt lgkmcnt(0)
	v_cvt_pk_bf16_f32 v22, v22, v23
	ds_read2_b32 v[24:25], v54 offset0:134 offset1:199
	s_waitcnt lgkmcnt(0)
	v_cvt_pk_bf16_f32 v23, v24, v25
	v_lshl_add_u64 v[28:29], v[26:27], 0, v[2:3]
	ds_read2_b32 v[24:25], v37 offset0:8 offset1:73
	global_store_dwordx4 v[28:29], v[20:23], off
	v_or_b32_e32 v2, s4, v38
	v_lshlrev_b32_e32 v2, 13, v2
	s_waitcnt lgkmcnt(0)
	v_cvt_pk_bf16_f32 v20, v24, v25
	ds_read2_b32 v[22:23], v37 offset0:138 offset1:203
	s_waitcnt lgkmcnt(0)
	v_cvt_pk_bf16_f32 v21, v22, v23
	ds_read2_b32 v[22:23], v54 offset0:12 offset1:77
	s_waitcnt lgkmcnt(0)
	v_cvt_pk_bf16_f32 v22, v22, v23
	ds_read2_b32 v[24:25], v54 offset0:142 offset1:207
	s_waitcnt lgkmcnt(0)
	v_cvt_pk_bf16_f32 v23, v24, v25
	v_lshl_add_u64 v[28:29], v[26:27], 0, v[2:3]
	ds_read2_b32 v[24:25], v37 offset0:16 offset1:81
	global_store_dwordx4 v[28:29], v[20:23], off
	v_or_b32_e32 v2, s4, v39
	v_lshlrev_b32_e32 v2, 13, v2
	s_waitcnt lgkmcnt(0)
	v_cvt_pk_bf16_f32 v20, v24, v25
	ds_read2_b32 v[22:23], v37 offset0:146 offset1:211
	s_waitcnt lgkmcnt(0)
	v_cvt_pk_bf16_f32 v21, v22, v23
	ds_read2_b32 v[22:23], v54 offset0:20 offset1:85
	s_waitcnt lgkmcnt(0)
	v_cvt_pk_bf16_f32 v22, v22, v23
	ds_read2_b32 v[24:25], v54 offset0:150 offset1:215
	s_waitcnt lgkmcnt(0)
	v_cvt_pk_bf16_f32 v23, v24, v25
	v_lshl_add_u64 v[28:29], v[26:27], 0, v[2:3]
	ds_read2_b32 v[24:25], v37 offset0:24 offset1:89
	global_store_dwordx4 v[28:29], v[20:23], off
	v_or_b32_e32 v2, s4, v40
	v_lshlrev_b32_e32 v2, 13, v2
	s_waitcnt lgkmcnt(0)
	v_cvt_pk_bf16_f32 v20, v24, v25
	ds_read2_b32 v[22:23], v37 offset0:154 offset1:219
	s_waitcnt lgkmcnt(0)
	v_cvt_pk_bf16_f32 v21, v22, v23
	ds_read2_b32 v[22:23], v54 offset0:28 offset1:93
	s_waitcnt lgkmcnt(0)
	v_cvt_pk_bf16_f32 v22, v22, v23
	ds_read2_b32 v[24:25], v54 offset0:158 offset1:223
	s_waitcnt lgkmcnt(0)
	v_cvt_pk_bf16_f32 v23, v24, v25
	v_lshl_add_u64 v[28:29], v[26:27], 0, v[2:3]
	ds_read2_b32 v[24:25], v37 offset0:32 offset1:97
	global_store_dwordx4 v[28:29], v[20:23], off
	v_or_b32_e32 v2, s4, v41
	v_lshlrev_b32_e32 v2, 13, v2
	s_waitcnt lgkmcnt(0)
	v_cvt_pk_bf16_f32 v20, v24, v25
	ds_read2_b32 v[22:23], v37 offset0:162 offset1:227
	s_waitcnt lgkmcnt(0)
	v_cvt_pk_bf16_f32 v21, v22, v23
	ds_read2_b32 v[22:23], v54 offset0:36 offset1:101
	s_waitcnt lgkmcnt(0)
	v_cvt_pk_bf16_f32 v22, v22, v23
	ds_read2_b32 v[24:25], v54 offset0:166 offset1:231
	s_waitcnt lgkmcnt(0)
	v_cvt_pk_bf16_f32 v23, v24, v25
	v_lshl_add_u64 v[28:29], v[26:27], 0, v[2:3]
	ds_read2_b32 v[24:25], v37 offset0:40 offset1:105
	global_store_dwordx4 v[28:29], v[20:23], off
	v_or_b32_e32 v2, s4, v42
	v_lshlrev_b32_e32 v2, 13, v2
	s_waitcnt lgkmcnt(0)
	v_cvt_pk_bf16_f32 v20, v24, v25
	ds_read2_b32 v[22:23], v37 offset0:170 offset1:235
	s_waitcnt lgkmcnt(0)
	v_cvt_pk_bf16_f32 v21, v22, v23
	ds_read2_b32 v[22:23], v54 offset0:44 offset1:109
	s_waitcnt lgkmcnt(0)
	v_cvt_pk_bf16_f32 v22, v22, v23
	ds_read2_b32 v[24:25], v54 offset0:174 offset1:239
	s_waitcnt lgkmcnt(0)
	v_cvt_pk_bf16_f32 v23, v24, v25
	v_lshl_add_u64 v[28:29], v[26:27], 0, v[2:3]
	ds_read2_b32 v[24:25], v37 offset0:48 offset1:113
	global_store_dwordx4 v[28:29], v[20:23], off
	v_or_b32_e32 v2, s4, v43
	v_lshlrev_b32_e32 v2, 13, v2
	s_waitcnt lgkmcnt(0)
	v_cvt_pk_bf16_f32 v20, v24, v25
	ds_read2_b32 v[22:23], v37 offset0:178 offset1:243
	s_waitcnt lgkmcnt(0)
	v_cvt_pk_bf16_f32 v21, v22, v23
	ds_read2_b32 v[22:23], v54 offset0:52 offset1:117
	s_waitcnt lgkmcnt(0)
	v_cvt_pk_bf16_f32 v22, v22, v23
	ds_read2_b32 v[24:25], v54 offset0:182 offset1:247
	s_waitcnt lgkmcnt(0)
	v_cvt_pk_bf16_f32 v23, v24, v25
	v_lshl_add_u64 v[28:29], v[26:27], 0, v[2:3]
	ds_read2_b32 v[24:25], v37 offset0:56 offset1:121
	global_store_dwordx4 v[28:29], v[20:23], off
	v_or_b32_e32 v2, s4, v44
	v_lshlrev_b32_e32 v2, 13, v2
	s_waitcnt lgkmcnt(0)
	v_cvt_pk_bf16_f32 v20, v24, v25
	ds_read2_b32 v[22:23], v37 offset0:186 offset1:251
	s_waitcnt lgkmcnt(0)
	v_cvt_pk_bf16_f32 v21, v22, v23
	ds_read2_b32 v[22:23], v54 offset0:60 offset1:125
	s_waitcnt lgkmcnt(0)
	v_cvt_pk_bf16_f32 v22, v22, v23
	ds_read2_b32 v[24:25], v54 offset0:190 offset1:255
	s_waitcnt lgkmcnt(0)
	v_cvt_pk_bf16_f32 v23, v24, v25
	v_lshl_add_u64 v[24:25], v[26:27], 0, v[2:3]
	global_store_dwordx4 v[24:25], v[20:23], off
	s_waitcnt lgkmcnt(0)

; #define GAS __attribute__((address_space(1)))
; #define LAS __attribute__((address_space(3)))
; #define LDS_WAIT() asm volatile("s_waitcnt lgkmcnt(0)" ::: "memory")
; __device__ __forceinline__ unsigned pk2(float lo, float hi) { return pg8::cvt_pk_bf16(lo, hi); }
; __device__ __forceinline__ void p0_transpose_item(const float* W, int K, int N, bf16r* WT, LAS float* scr, int item, int lane) {
;     const int nblk = N / 64, kb = item / nblk, nb = item % nblk, k0 = 64 * kb, n0 = 64 * nb;
; #pragma unroll 8
;     for (int i = 0; i < 32; ++i) { const int kk = 2 * i + (lane >> 5); const f32x2 v = *(const f32x2*)(W + (size_t)(k0 + kk) * N + n0 + 2 * (lane & 31)); scr[kk * 65 + 2 * (lane & 31)] = v.x; scr[kk * 65 + 2 * (lane & 31) + 1] = v.y; }
;     LDS_WAIT(); asm volatile("" ::: "memory");
;     const int c = lane & 7;
; #pragma unroll
;     for (int j = 0; j < 8; ++j) { const int n = (lane >> 3) + 8 * j; const LAS float* s = scr + (8 * c) * 65 + n;
;         v4u o; o.x = pk2(s[0 * 65], s[1 * 65]); o.y = pk2(s[2 * 65], s[3 * 65]); o.z = pk2(s[4 * 65], s[5 * 65]); o.w = pk2(s[6 * 65], s[7 * 65]);
;         *(GAS v4u*)(WT + (size_t)(n0 + n) * K + k0 + 8 * c) = o; }
;     LDS_WAIT(); asm volatile("" ::: "memory");
; }
.LBB0_29:
	v_lshl_add_u64 v[56:57], v[34:35], 0, s[4:5]
	v_lshl_add_u64 v[58:59], v[32:33], 0, s[4:5]
	v_lshl_add_u64 v[60:61], v[30:31], 0, s[4:5]
	v_lshl_add_u64 v[62:63], v[28:29], 0, s[4:5]
	v_lshl_add_u64 v[64:65], v[26:27], 0, s[4:5]
	v_lshl_add_u64 v[66:67], v[24:25], 0, s[4:5]
	v_lshl_add_u64 v[68:69], v[22:23], 0, s[4:5]
	v_lshl_add_u64 v[70:71], v[20:21], 0, s[4:5]
	global_load_dwordx2 v[72:73], v[56:57], off nt
	global_load_dwordx2 v[74:75], v[58:59], off nt
	global_load_dwordx2 v[76:77], v[60:61], off nt
	global_load_dwordx2 v[78:79], v[62:63], off nt
	global_load_dwordx2 v[80:81], v[64:65], off nt
	global_load_dwordx2 v[82:83], v[66:67], off nt
	global_load_dwordx2 v[84:85], v[68:69], off nt
	global_load_dwordx2 v[86:87], v[70:71], off nt
	s_add_u32 s4, s4, 0x40000
	s_addc_u32 s5, s5, 0
	v_add_u32_e32 v55, 0x410, v2
	v_add_u32_e32 v56, 0x618, v2
	v_add_u32_e32 v57, 0x820, v2
	v_add_u32_e32 v58, 0xa28, v2
	v_add_u32_e32 v59, 0xc30, v2
	v_add_u32_e32 v60, 0xe38, v2
	s_cmp_lg_u32 s4, 0x100000
	s_waitcnt vmcnt(7)
	ds_write2_b32 v2, v72, v73 offset1:1
	s_waitcnt vmcnt(6)
	ds_write2_b32 v2, v74, v75 offset0:130 offset1:131
	s_waitcnt vmcnt(5)
	ds_write2_b32 v55, v76, v77 offset1:1
	s_waitcnt vmcnt(4)
	ds_write2_b32 v56, v78, v79 offset1:1
	s_waitcnt vmcnt(3)
	ds_write2_b32 v57, v80, v81 offset1:1
	s_waitcnt vmcnt(2)
	ds_write2_b32 v58, v82, v83 offset1:1
	s_waitcnt vmcnt(1)
	ds_write2_b32 v59, v84, v85 offset1:1
	s_waitcnt vmcnt(0)
	ds_write2_b32 v60, v86, v87 offset1:1
	v_add_u32_e32 v2, 0x1040, v2
	s_cbranch_scc1 .LBB0_29
	s_waitcnt lgkmcnt(0)
	s_add_i32 s2, s39, 0xc800
	s_lshl_b32 s4, s39, 6
	ds_read2_b32 v[20:21], v37 offset1:65
	s_and_b32 s2, s2, 0xffc0
	s_and_b32 s4, s4, 0xfc0
	s_waitcnt lgkmcnt(0)
	v_cvt_pk_bf16_f32 v20, v20, v21
	ds_read2_b32 v[22:23], v37 offset0:130 offset1:195
	s_lshl_b32 s2, s2, 1
	v_or_b32_e32 v2, s4, v36
	s_waitcnt lgkmcnt(0)
	v_cvt_pk_bf16_f32 v21, v22, v23
	ds_read2_b32 v[22:23], v54 offset0:4 offset1:69
	v_lshl_add_u64 v[26:27], v[10:11], 0, s[2:3]
	v_lshlrev_b32_e32 v2, 13, v2
	s_waitcnt lgkmcnt(0)
	v_cvt_pk_bf16_f32 v22, v22, v23
	ds_read2_b32 v[24:25], v54 offset0:134 offset1:199
	s_waitcnt lgkmcnt(0)
	v_cvt_pk_bf16_f32 v23, v24, v25
	v_lshl_add_u64 v[28:29], v[26:27], 0, v[2:3]
	ds_read2_b32 v[24:25], v37 offset0:8 offset1:73
	global_store_dwordx4 v[28:29], v[20:23], off
	v_or_b32_e32 v2, s4, v38
	v_lshlrev_b32_e32 v2, 13, v2
	s_waitcnt lgkmcnt(0)
	v_cvt_pk_bf16_f32 v20, v24, v25
	ds_read2_b32 v[22:23], v37 offset0:138 offset1:203
	s_waitcnt lgkmcnt(0)
	v_cvt_pk_bf16_f32 v21, v22, v23
	ds_read2_b32 v[22:23], v54 offset0:12 offset1:77
	s_waitcnt lgkmcnt(0)
	v_cvt_pk_bf16_f32 v22, v22, v23
	ds_read2_b32 v[24:25], v54 offset0:142 offset1:207
	s_waitcnt lgkmcnt(0)
	v_cvt_pk_bf16_f32 v23, v24, v25
	v_lshl_add_u64 v[28:29], v[26:27], 0, v[2:3]
	ds_read2_b32 v[24:25], v37 offset0:16 offset1:81
	global_store_dwordx4 v[28:29], v[20:23], off
	v_or_b32_e32 v2, s4, v39
	v_lshlrev_b32_e32 v2, 13, v2
	s_waitcnt lgkmcnt(0)
	v_cvt_pk_bf16_f32 v20, v24, v25
	ds_read2_b32 v[22:23], v37 offset0:146 offset1:211
	s_waitcnt lgkmcnt(0)
	v_cvt_pk_bf16_f32 v21, v22, v23
	ds_read2_b32 v[22:23], v54 offset0:20 offset1:85
	s_waitcnt lgkmcnt(0)
	v_cvt_pk_bf16_f32 v22, v22, v23
	ds_read2_b32 v[24:25], v54 offset0:150 offset1:215
	s_waitcnt lgkmcnt(0)
	v_cvt_pk_bf16_f32 v23, v24, v25
	v_lshl_add_u64 v[28:29], v[26:27], 0, v[2:3]
	ds_read2_b32 v[24:25], v37 offset0:24 offset1:89
	global_store_dwordx4 v[28:29], v[20:23], off
	v_or_b32_e32 v2, s4, v40
	v_lshlrev_b32_e32 v2, 13, v2
	s_waitcnt lgkmcnt(0)
	v_cvt_pk_bf16_f32 v20, v24, v25
	ds_read2_b32 v[22:23], v37 offset0:154 offset1:219
	s_waitcnt lgkmcnt(0)
	v_cvt_pk_bf16_f32 v21, v22, v23
	ds_read2_b32 v[22:23], v54 offset0:28 offset1:93
	s_waitcnt lgkmcnt(0)
	v_cvt_pk_bf16_f32 v22, v22, v23
	ds_read2_b32 v[24:25], v54 offset0:158 offset1:223
	s_waitcnt lgkmcnt(0)
	v_cvt_pk_bf16_f32 v23, v24, v25
	v_lshl_add_u64 v[28:29], v[26:27], 0, v[2:3]
	ds_read2_b32 v[24:25], v37 offset0:32 offset1:97
	global_store_dwordx4 v[28:29], v[20:23], off
	v_or_b32_e32 v2, s4, v41
	v_lshlrev_b32_e32 v2, 13, v2
	s_waitcnt lgkmcnt(0)
	v_cvt_pk_bf16_f32 v20, v24, v25
	ds_read2_b32 v[22:23], v37 offset0:162 offset1:227
	s_waitcnt lgkmcnt(0)
	v_cvt_pk_bf16_f32 v21, v22, v23
	ds_read2_b32 v[22:23], v54 offset0:36 offset1:101
	s_waitcnt lgkmcnt(0)
	v_cvt_pk_bf16_f32 v22, v22, v23
	ds_read2_b32 v[24:25], v54 offset0:166 offset1:231
	s_waitcnt lgkmcnt(0)
	v_cvt_pk_bf16_f32 v23, v24, v25
	v_lshl_add_u64 v[28:29], v[26:27], 0, v[2:3]
	ds_read2_b32 v[24:25], v37 offset0:40 offset1:105
	global_store_dwordx4 v[28:29], v[20:23], off
	v_or_b32_e32 v2, s4, v42
	v_lshlrev_b32_e32 v2, 13, v2
	s_waitcnt lgkmcnt(0)
	v_cvt_pk_bf16_f32 v20, v24, v25
	ds_read2_b32 v[22:23], v37 offset0:170 offset1:235
	s_waitcnt lgkmcnt(0)
	v_cvt_pk_bf16_f32 v21, v22, v23
	ds_read2_b32 v[22:23], v54 offset0:44 offset1:109
	s_waitcnt lgkmcnt(0)
	v_cvt_pk_bf16_f32 v22, v22, v23
	ds_read2_b32 v[24:25], v54 offset0:174 offset1:239
	s_waitcnt lgkmcnt(0)
	v_cvt_pk_bf16_f32 v23, v24, v25
	v_lshl_add_u64 v[28:29], v[26:27], 0, v[2:3]
	ds_read2_b32 v[24:25], v37 offset0:48 offset1:113
	global_store_dwordx4 v[28:29], v[20:23], off
	v_or_b32_e32 v2, s4, v43
	v_lshlrev_b32_e32 v2, 13, v2
	s_waitcnt lgkmcnt(0)
	v_cvt_pk_bf16_f32 v20, v24, v25
	ds_read2_b32 v[22:23], v37 offset0:178 offset1:243
	s_waitcnt lgkmcnt(0)
	v_cvt_pk_bf16_f32 v21, v22, v23
	ds_read2_b32 v[22:23], v54 offset0:52 offset1:117
	s_waitcnt lgkmcnt(0)
	v_cvt_pk_bf16_f32 v22, v22, v23
	ds_read2_b32 v[24:25], v54 offset0:182 offset1:247
	s_waitcnt lgkmcnt(0)
	v_cvt_pk_bf16_f32 v23, v24, v25
	v_lshl_add_u64 v[28:29], v[26:27], 0, v[2:3]
	ds_read2_b32 v[24:25], v37 offset0:56 offset1:121
	global_store_dwordx4 v[28:29], v[20:23], off
	v_or_b32_e32 v2, s4, v44
	v_lshlrev_b32_e32 v2, 13, v2
	s_waitcnt lgkmcnt(0)
	v_cvt_pk_bf16_f32 v20, v24, v25
	ds_read2_b32 v[22:23], v37 offset0:186 offset1:251
	s_waitcnt lgkmcnt(0)
	v_cvt_pk_bf16_f32 v21, v22, v23
	ds_read2_b32 v[22:23], v54 offset0:60 offset1:125
	s_waitcnt lgkmcnt(0)
	v_cvt_pk_bf16_f32 v22, v22, v23
	ds_read2_b32 v[24:25], v54 offset0:190 offset1:255
	s_waitcnt lgkmcnt(0)
	v_cvt_pk_bf16_f32 v23, v24, v25
	v_lshl_add_u64 v[24:25], v[26:27], 0, v[2:3]
	global_store_dwordx4 v[24:25], v[20:23], off
	s_waitcnt lgkmcnt(0)

; #define GAS __attribute__((address_space(1)))
; #define LAS __attribute__((address_space(3)))
; #define LDS_WAIT() asm volatile("s_waitcnt lgkmcnt(0)" ::: "memory")
; __device__ __forceinline__ unsigned pk2(float lo, float hi) { return pg8::cvt_pk_bf16(lo, hi); }
; __device__ __forceinline__ void p0_transpose_item(const float* W, int K, int N, bf16r* WT, LAS float* scr, int item, int lane) {
;     const int nblk = N / 64, kb = item / nblk, nb = item % nblk, k0 = 64 * kb, n0 = 64 * nb;
; #pragma unroll 8
;     for (int i = 0; i < 32; ++i) { const int kk = 2 * i + (lane >> 5); const f32x2 v = *(const f32x2*)(W + (size_t)(k0 + kk) * N + n0 + 2 * (lane & 31)); scr[kk * 65 + 2 * (lane & 31)] = v.x; scr[kk * 65 + 2 * (lane & 31) + 1] = v.y; }
;     LDS_WAIT(); asm volatile("" ::: "memory");
;     const int c = lane & 7;
; #pragma unroll
;     for (int j = 0; j < 8; ++j) { const int n = (lane >> 3) + 8 * j; const LAS float* s = scr + (8 * c) * 65 + n;
;         v4u o; o.x = pk2(s[0 * 65], s[1 * 65]); o.y = pk2(s[2 * 65], s[3 * 65]); o.z = pk2(s[4 * 65], s[5 * 65]); o.w = pk2(s[6 * 65], s[7 * 65]);
;         *(GAS v4u*)(WT + (size_t)(n0 + n) * K + k0 + 8 * c) = o; }
;     LDS_WAIT(); asm volatile("" ::: "memory");
; }
.LBB0_34:
	v_lshl_add_u64 v[56:57], v[34:35], 0, s[18:19]
	v_lshl_add_u64 v[58:59], v[32:33], 0, s[18:19]
	v_lshl_add_u64 v[60:61], v[30:31], 0, s[18:19]
	v_lshl_add_u64 v[62:63], v[28:29], 0, s[18:19]
	v_lshl_add_u64 v[64:65], v[26:27], 0, s[18:19]
	v_lshl_add_u64 v[66:67], v[24:25], 0, s[18:19]
	v_lshl_add_u64 v[68:69], v[22:23], 0, s[18:19]
	v_lshl_add_u64 v[70:71], v[20:21], 0, s[18:19]
	global_load_dwordx2 v[72:73], v[56:57], off nt
	global_load_dwordx2 v[74:75], v[58:59], off nt
	global_load_dwordx2 v[76:77], v[60:61], off nt
	global_load_dwordx2 v[78:79], v[62:63], off nt
	global_load_dwordx2 v[80:81], v[64:65], off nt
	global_load_dwordx2 v[82:83], v[66:67], off nt
	global_load_dwordx2 v[84:85], v[68:69], off nt
	global_load_dwordx2 v[86:87], v[70:71], off nt
	s_add_u32 s18, s18, 0xe0000
	s_addc_u32 s19, s19, 0
	v_add_u32_e32 v55, 0x410, v2
	v_add_u32_e32 v56, 0x618, v2
	v_add_u32_e32 v57, 0x820, v2
	v_add_u32_e32 v58, 0xa28, v2
	v_add_u32_e32 v59, 0xc30, v2
	v_add_u32_e32 v60, 0xe38, v2
	s_cmp_lg_u32 s18, 0x380000
	s_waitcnt vmcnt(7)
	ds_write2_b32 v2, v72, v73 offset1:1
	s_waitcnt vmcnt(6)
	ds_write2_b32 v2, v74, v75 offset0:130 offset1:131
	s_waitcnt vmcnt(5)
	ds_write2_b32 v55, v76, v77 offset1:1
	s_waitcnt vmcnt(4)
	ds_write2_b32 v56, v78, v79 offset1:1
	s_waitcnt vmcnt(3)
	ds_write2_b32 v57, v80, v81 offset1:1
	s_waitcnt vmcnt(2)
	ds_write2_b32 v58, v82, v83 offset1:1
	s_waitcnt vmcnt(1)
	ds_write2_b32 v59, v84, v85 offset1:1
	s_waitcnt vmcnt(0)
	ds_write2_b32 v60, v86, v87 offset1:1
	v_add_u32_e32 v2, 0x1040, v2
	s_cbranch_scc1 .LBB0_34
	s_waitcnt lgkmcnt(0)
	v_or_b32_e32 v26, s4, v36
	ds_read2_b32 v[20:21], v37 offset1:65
	s_ashr_i32 s7, s6, 31
	v_ashrrev_i32_e32 v27, 31, v26
	s_waitcnt lgkmcnt(0)
	v_cvt_pk_bf16_f32 v20, v20, v21
	ds_read2_b32 v[22:23], v37 offset0:130 offset1:195
	v_lshl_add_u64 v[28:29], s[6:7], 1, v[4:5]
	v_lshlrev_b64 v[26:27], 13, v[26:27]
	s_waitcnt lgkmcnt(0)
	v_cvt_pk_bf16_f32 v21, v22, v23
	ds_read2_b32 v[22:23], v54 offset0:4 offset1:69
	v_lshl_add_u64 v[26:27], v[28:29], 0, v[26:27]
	s_waitcnt lgkmcnt(0)
	v_cvt_pk_bf16_f32 v22, v22, v23
	ds_read2_b32 v[24:25], v54 offset0:134 offset1:199
	s_waitcnt lgkmcnt(0)
	v_cvt_pk_bf16_f32 v23, v24, v25
	global_store_dwordx4 v[26:27], v[20:23], off
	v_or_b32_e32 v26, s4, v38
	v_ashrrev_i32_e32 v27, 31, v26
	ds_read2_b32 v[24:25], v37 offset0:8 offset1:73
	s_waitcnt lgkmcnt(0)
	v_cvt_pk_bf16_f32 v20, v24, v25
	ds_read2_b32 v[22:23], v37 offset0:138 offset1:203
	v_lshlrev_b64 v[26:27], 13, v[26:27]
	s_waitcnt lgkmcnt(0)
	v_cvt_pk_bf16_f32 v21, v22, v23
	ds_read2_b32 v[22:23], v54 offset0:12 offset1:77
	v_lshl_add_u64 v[26:27], v[28:29], 0, v[26:27]
	s_waitcnt lgkmcnt(0)
	v_cvt_pk_bf16_f32 v22, v22, v23
	ds_read2_b32 v[24:25], v54 offset0:142 offset1:207
	s_waitcnt lgkmcnt(0)
	v_cvt_pk_bf16_f32 v23, v24, v25
	global_store_dwordx4 v[26:27], v[20:23], off
	v_or_b32_e32 v26, s4, v39
	v_ashrrev_i32_e32 v27, 31, v26
	ds_read2_b32 v[24:25], v37 offset0:16 offset1:81
	s_waitcnt lgkmcnt(0)
	v_cvt_pk_bf16_f32 v20, v24, v25
	ds_read2_b32 v[22:23], v37 offset0:146 offset1:211
	v_lshlrev_b64 v[26:27], 13, v[26:27]
	s_waitcnt lgkmcnt(0)
	v_cvt_pk_bf16_f32 v21, v22, v23
	ds_read2_b32 v[22:23], v54 offset0:20 offset1:85
	v_lshl_add_u64 v[26:27], v[28:29], 0, v[26:27]
	s_waitcnt lgkmcnt(0)
	v_cvt_pk_bf16_f32 v22, v22, v23
	ds_read2_b32 v[24:25], v54 offset0:150 offset1:215
	s_waitcnt lgkmcnt(0)
	v_cvt_pk_bf16_f32 v23, v24, v25
	global_store_dwordx4 v[26:27], v[20:23], off
	v_or_b32_e32 v26, s4, v40
	v_ashrrev_i32_e32 v27, 31, v26
	ds_read2_b32 v[24:25], v37 offset0:24 offset1:89
	s_waitcnt lgkmcnt(0)
	v_cvt_pk_bf16_f32 v20, v24, v25
	ds_read2_b32 v[22:23], v37 offset0:154 offset1:219
	v_lshlrev_b64 v[26:27], 13, v[26:27]
	s_waitcnt lgkmcnt(0)
	v_cvt_pk_bf16_f32 v21, v22, v23
	ds_read2_b32 v[22:23], v54 offset0:28 offset1:93
	v_lshl_add_u64 v[26:27], v[28:29], 0, v[26:27]
	s_waitcnt lgkmcnt(0)
	v_cvt_pk_bf16_f32 v22, v22, v23
	ds_read2_b32 v[24:25], v54 offset0:158 offset1:223
	s_waitcnt lgkmcnt(0)
	v_cvt_pk_bf16_f32 v23, v24, v25
	global_store_dwordx4 v[26:27], v[20:23], off
	v_or_b32_e32 v26, s4, v41
	v_ashrrev_i32_e32 v27, 31, v26
	ds_read2_b32 v[24:25], v37 offset0:32 offset1:97
	s_waitcnt lgkmcnt(0)
	v_cvt_pk_bf16_f32 v20, v24, v25
	ds_read2_b32 v[22:23], v37 offset0:162 offset1:227
	v_lshlrev_b64 v[26:27], 13, v[26:27]
	s_waitcnt lgkmcnt(0)
	v_cvt_pk_bf16_f32 v21, v22, v23
	ds_read2_b32 v[22:23], v54 offset0:36 offset1:101
	v_lshl_add_u64 v[26:27], v[28:29], 0, v[26:27]
	s_waitcnt lgkmcnt(0)
	v_cvt_pk_bf16_f32 v22, v22, v23
	ds_read2_b32 v[24:25], v54 offset0:166 offset1:231
	s_waitcnt lgkmcnt(0)
	v_cvt_pk_bf16_f32 v23, v24, v25
	global_store_dwordx4 v[26:27], v[20:23], off
	v_or_b32_e32 v26, s4, v42
	v_ashrrev_i32_e32 v27, 31, v26
	ds_read2_b32 v[24:25], v37 offset0:40 offset1:105
	s_waitcnt lgkmcnt(0)
	v_cvt_pk_bf16_f32 v20, v24, v25
	ds_read2_b32 v[22:23], v37 offset0:170 offset1:235
	v_lshlrev_b64 v[26:27], 13, v[26:27]
	s_waitcnt lgkmcnt(0)
	v_cvt_pk_bf16_f32 v21, v22, v23
	ds_read2_b32 v[22:23], v54 offset0:44 offset1:109
	v_lshl_add_u64 v[26:27], v[28:29], 0, v[26:27]
	s_waitcnt lgkmcnt(0)
	v_cvt_pk_bf16_f32 v22, v22, v23
	ds_read2_b32 v[24:25], v54 offset0:174 offset1:239
	s_waitcnt lgkmcnt(0)
	v_cvt_pk_bf16_f32 v23, v24, v25
	global_store_dwordx4 v[26:27], v[20:23], off
	v_or_b32_e32 v26, s4, v43
	ds_read2_b32 v[24:25], v37 offset0:48 offset1:113
	s_waitcnt lgkmcnt(0)
	v_cvt_pk_bf16_f32 v20, v24, v25
	ds_read2_b32 v[22:23], v37 offset0:178 offset1:243
	v_ashrrev_i32_e32 v27, 31, v26
	s_waitcnt lgkmcnt(0)
	v_cvt_pk_bf16_f32 v21, v22, v23
	ds_read2_b32 v[22:23], v54 offset0:52 offset1:117
	v_lshlrev_b64 v[26:27], 13, v[26:27]
	s_waitcnt lgkmcnt(0)
	v_cvt_pk_bf16_f32 v22, v22, v23
	ds_read2_b32 v[24:25], v54 offset0:182 offset1:247
	s_waitcnt lgkmcnt(0)
	v_cvt_pk_bf16_f32 v23, v24, v25
	v_lshl_add_u64 v[26:27], v[28:29], 0, v[26:27]
	ds_read2_b32 v[24:25], v37 offset0:56 offset1:121
	global_store_dwordx4 v[26:27], v[20:23], off
	v_or_b32_e32 v26, s4, v44
	v_ashrrev_i32_e32 v27, 31, v26
	s_waitcnt lgkmcnt(0)
	v_cvt_pk_bf16_f32 v20, v24, v25
	ds_read2_b32 v[22:23], v37 offset0:186 offset1:251
	s_waitcnt lgkmcnt(0)
	v_cvt_pk_bf16_f32 v21, v22, v23
	ds_read2_b32 v[22:23], v54 offset0:60 offset1:125
	s_waitcnt lgkmcnt(0)
	v_cvt_pk_bf16_f32 v22, v22, v23
	ds_read2_b32 v[24:25], v54 offset0:190 offset1:255
	v_lshlrev_b64 v[26:27], 13, v[26:27]
	s_waitcnt lgkmcnt(0)
	v_cvt_pk_bf16_f32 v23, v24, v25
	v_lshl_add_u64 v[24:25], v[28:29], 0, v[26:27]
	global_store_dwordx4 v[24:25], v[20:23], off
	s_waitcnt lgkmcnt(0)
	s_branch .LBB0_15

; template <bool OUT_BF16> __device__ __forceinline__ void rms_row(const float* xrow, const float* g, void* orow, int lane, float* ssq = nullptr) {
;     const f32x4* xr = (const f32x4*)xrow + lane;
;     f32x4 v[16]; float s = 0.f;
; #pragma unroll
;     for (int j = 0; j < 16; ++j) { v[j] = xr[64 * j]; s += (v[j].x * v[j].x + v[j].y * v[j].y) + (v[j].z * v[j].z + v[j].w * v[j].w); }
;     const float tot = wave_sum(s);
.LBB0_49:
	global_load_dwordx4 v[14:17], v[94:95], off nt
	global_load_dwordx4 v[10:13], v[94:95], off offset:1024 nt
	global_load_dwordx4 v[6:9], v[94:95], off offset:2048 nt
	global_load_dwordx4 v[2:5], v[94:95], off offset:3072 nt
	v_add_co_u32_e32 v98, vcc, s12, v94
	s_add_i32 s26, s26, s36
	s_nop 0
	v_addc_co_u32_e32 v99, vcc, 0, v95, vcc
	v_add_co_u32_e32 v100, vcc, s13, v94
	s_cmpk_gt_i32 s26, 0x3fff
	s_nop 0
	v_addc_co_u32_e32 v101, vcc, 0, v95, vcc
	v_add_co_u32_e32 v102, vcc, s14, v94
	s_waitcnt vmcnt(2)
	v_pk_mul_f32 v[114:115], v[10:11], v[10:11]
	v_addc_co_u32_e32 v103, vcc, 0, v95, vcc
	global_load_dwordx4 v[110:113], v[68:69], off nt
	global_load_dwordx4 v[62:65], v[100:101], off offset:-4096 nt
	global_load_dwordx4 v[54:57], v[98:99], off offset:2048 nt
	global_load_dwordx4 v[58:61], v[98:99], off offset:1024 nt
	global_load_dwordx4 v[50:53], v[98:99], off offset:3072 nt
	global_load_dwordx4 v[42:45], v[100:101], off offset:1024 nt
	global_load_dwordx4 v[46:49], v[100:101], off nt
	global_load_dwordx4 v[38:41], v[100:101], off offset:2048 nt
	global_load_dwordx4 v[30:33], v[102:103], off nt
	global_load_dwordx4 v[34:37], v[100:101], off offset:3072 nt
	global_load_dwordx4 v[26:29], v[102:103], off offset:1024 nt
	global_load_dwordx4 v[18:21], v[102:103], off offset:3072 nt
	global_load_dwordx4 v[22:25], v[102:103], off offset:2048 nt
	v_pk_mul_f32 v[98:99], v[16:17], v[16:17]
	v_pk_mul_f32 v[100:101], v[14:15], v[14:15]
	v_pk_mul_f32 v[102:103], v[12:13], v[12:13]
	v_pk_mov_b32 v[120:121], v[100:101], v[98:99] op_sel:[1,0]
	v_mov_b32_e32 v101, v99
	v_pk_mov_b32 v[98:99], v[114:115], v[102:103] op_sel:[1,0]
	v_mov_b32_e32 v115, v103
	s_waitcnt vmcnt(14)
	v_mul_f32_e32 v116, v7, v7
	v_mul_f32_e32 v118, v9, v9
	v_pk_add_f32 v[100:101], v[120:121], v[100:101]
	v_pk_add_f32 v[98:99], v[98:99], v[114:115]
	s_waitcnt vmcnt(13)
	v_mul_f32_e32 v149, v2, v2
	v_mul_f32_e32 v151, v3, v3
	v_mul_f32_e32 v125, v4, v4
	v_mul_f32_e32 v127, v5, v5
	v_pk_fma_f32 v[102:103], v[6:7], v[6:7], v[116:117] op_sel_hi:[1,1,0]
	v_pk_fma_f32 v[116:117], v[8:9], v[8:9], v[118:119] op_sel_hi:[1,1,0]
	v_pk_add_f32 v[100:101], v[100:101], v[100:101] op_sel:[0,1] op_sel_hi:[1,0]
	v_pk_add_f32 v[98:99], v[98:99], v[98:99] op_sel:[0,1] op_sel_hi:[1,0]
	v_mov_b32_e32 v103, v125
	v_mov_b32_e32 v117, v127
	v_mov_b32_e32 v101, v149
	v_mov_b32_e32 v99, v151
	v_pk_add_f32 v[102:103], v[102:103], v[116:117]
	v_pk_add_f32 v[98:99], v[100:101], v[98:99]
	v_lshl_add_u64 v[94:95], v[94:95], 0, s[4:5]
	v_pk_add_f32 v[98:99], v[98:99], v[102:103]
	s_waitcnt vmcnt(11)
	v_pk_mul_f32 v[118:119], v[64:65], v[64:65]
	v_pk_mul_f32 v[122:123], v[62:63], v[62:63]
	s_waitcnt vmcnt(9)
	v_mul_f32_e32 v124, v59, v59
	v_pk_mov_b32 v[114:115], v[122:123], v[118:119] op_sel:[1,0]
	v_mov_b32_e32 v123, v119
	v_mul_f32_e32 v126, v61, v61
	v_pk_add_f32 v[114:115], v[114:115], v[122:123]
	v_mul_f32_e32 v152, v54, v54
	v_mul_f32_e32 v153, v55, v55
	v_mul_f32_e32 v154, v56, v56
	v_mul_f32_e32 v155, v57, v57
	v_pk_fma_f32 v[118:119], v[58:59], v[58:59], v[124:125] op_sel_hi:[1,1,0]
	v_pk_fma_f32 v[120:121], v[60:61], v[60:61], v[126:127] op_sel_hi:[1,1,0]
	v_pk_add_f32 v[114:115], v[114:115], v[114:115] op_sel:[0,1] op_sel_hi:[1,0]
	v_pk_add_f32 v[98:99], v[98:99], v[98:99] op_sel:[0,1] op_sel_hi:[1,0]
	s_waitcnt vmcnt(8)
	v_pk_mul_f32 v[128:129], v[52:53], v[52:53]
	v_pk_mul_f32 v[130:131], v[50:51], v[50:51]
	v_mov_b32_e32 v119, v154
	v_mov_b32_e32 v121, v155
	v_mov_b32_e32 v115, v153
	v_mov_b32_e32 v99, v152
	v_pk_mov_b32 v[124:125], v[130:131], v[128:129] op_sel:[1,0]
	v_mov_b32_e32 v131, v129
	v_pk_add_f32 v[118:119], v[118:119], v[120:121]
	v_pk_add_f32 v[98:99], v[98:99], v[114:115]
	s_waitcnt vmcnt(6)
	v_mul_f32_e32 v132, v47, v47
	v_mul_f32_e32 v134, v49, v49
	v_pk_add_f32 v[116:117], v[124:125], v[130:131]
	v_pk_add_f32 v[98:99], v[98:99], v[118:119]
	v_mul_f32_e32 v156, v42, v42
	v_mul_f32_e32 v157, v43, v43
	v_mul_f32_e32 v158, v44, v44
	v_mul_f32_e32 v159, v45, v45
	v_pk_fma_f32 v[126:127], v[46:47], v[46:47], v[132:133] op_sel_hi:[1,1,0]
	v_pk_fma_f32 v[128:129], v[48:49], v[48:49], v[134:135] op_sel_hi:[1,1,0]
	v_pk_add_f32 v[116:117], v[116:117], v[116:117] op_sel:[0,1] op_sel_hi:[1,0]
	v_pk_add_f32 v[98:99], v[98:99], v[98:99] op_sel:[0,1] op_sel_hi:[1,0]
	s_waitcnt vmcnt(5)
	v_pk_mul_f32 v[136:137], v[40:41], v[40:41]
	v_pk_mul_f32 v[138:139], v[38:39], v[38:39]
	v_mov_b32_e32 v127, v158
	v_mov_b32_e32 v129, v159
	v_mov_b32_e32 v117, v157
	v_mov_b32_e32 v99, v156
	v_pk_mov_b32 v[132:133], v[138:139], v[136:137] op_sel:[1,0]
	v_mov_b32_e32 v139, v137
	v_pk_add_f32 v[120:121], v[126:127], v[128:129]
	v_pk_add_f32 v[98:99], v[98:99], v[116:117]
	s_waitcnt vmcnt(3)
	v_mul_f32_e32 v140, v35, v35
	v_mul_f32_e32 v142, v37, v37
	v_pk_add_f32 v[122:123], v[132:133], v[138:139]
	v_pk_add_f32 v[98:99], v[98:99], v[120:121]
	v_mul_f32_e32 v160, v30, v30
	v_mul_f32_e32 v161, v31, v31
	v_mul_f32_e32 v162, v32, v32
	v_mul_f32_e32 v163, v33, v33
	v_pk_fma_f32 v[134:135], v[34:35], v[34:35], v[140:141] op_sel_hi:[1,1,0]
	v_pk_fma_f32 v[136:137], v[36:37], v[36:37], v[142:143] op_sel_hi:[1,1,0]
	v_pk_add_f32 v[122:123], v[122:123], v[122:123] op_sel:[0,1] op_sel_hi:[1,0]
	v_pk_add_f32 v[98:99], v[98:99], v[98:99] op_sel:[0,1] op_sel_hi:[1,0]
	s_waitcnt vmcnt(2)
	v_pk_mul_f32 v[144:145], v[28:29], v[28:29]
	v_pk_mul_f32 v[146:147], v[26:27], v[26:27]
	v_mov_b32_e32 v135, v162
	v_mov_b32_e32 v137, v163
	v_mov_b32_e32 v123, v161
	v_mov_b32_e32 v99, v160
	v_pk_mov_b32 v[140:141], v[146:147], v[144:145] op_sel:[1,0]
	v_mov_b32_e32 v147, v145
	v_pk_add_f32 v[126:127], v[134:135], v[136:137]
	v_pk_add_f32 v[98:99], v[98:99], v[122:123]
	s_waitcnt vmcnt(0)
; __device__ __forceinline__ unsigned pk2(float lo, float hi) { return pg8::cvt_pk_bf16(lo, hi); }
; template <bool OUT_BF16> __device__ __forceinline__ void rms_row(const float* xrow, const float* g, void* orow, int lane, float* ssq = nullptr) {
;     ...
;     const float tot = wave_sum(s);
;     float rstd = 1.0f / sqrtf(tot * (1.0f / 4096.0f) + EPS);
;     if (ssq) { rstd = 1.0f; if (lane == 0) *ssq = tot; }
;     const f32x4* gr = (const f32x4*)g + lane;
; #pragma unroll
;     for (int j = 0; j < 16; ++j) { const f32x4 o = v[j] * rstd * gr[64 * j];
;         if (OUT_BF16) { v2u w; w.x = pk2(o.x, o.y); w.y = pk2(o.z, o.w); ((v2u*)orow)[64 * j + lane] = w; }
	v_mul_f32_e32 v148, v23, v23
	v_mul_f32_e32 v150, v25, v25
	v_pk_add_f32 v[124:125], v[140:141], v[146:147]
	v_pk_add_f32 v[98:99], v[98:99], v[126:127]
	v_mul_f32_e32 v164, v18, v18
	v_mul_f32_e32 v165, v19, v19
	v_mul_f32_e32 v166, v20, v20
	v_mul_f32_e32 v167, v21, v21
	v_pk_fma_f32 v[142:143], v[22:23], v[22:23], v[148:149] op_sel_hi:[1,1,0]
	v_pk_fma_f32 v[144:145], v[24:25], v[24:25], v[150:151] op_sel_hi:[1,1,0]
	v_pk_add_f32 v[124:125], v[124:125], v[124:125] op_sel:[0,1] op_sel_hi:[1,0]
	v_pk_add_f32 v[98:99], v[98:99], v[98:99] op_sel:[0,1] op_sel_hi:[1,0]
	v_mov_b32_e32 v143, v166
	v_mov_b32_e32 v145, v167
	v_mov_b32_e32 v125, v165
	v_mov_b32_e32 v99, v164
	v_pk_add_f32 v[128:129], v[142:143], v[144:145]
	v_pk_add_f32 v[98:99], v[98:99], v[124:125]
	s_nop 0
	v_pk_add_f32 v[98:99], v[98:99], v[128:129]
	s_nop 0
	v_add_f32_e32 v98, v98, v99
	ds_bpermute_b32 v99, v1, v98
	s_waitcnt lgkmcnt(0)
	v_add_f32_e32 v98, v98, v99
	ds_bpermute_b32 v99, v67, v98
	s_waitcnt lgkmcnt(0)
	v_add_f32_e32 v98, v98, v99
	ds_bpermute_b32 v99, v104, v98
	s_waitcnt lgkmcnt(0)
	v_add_f32_e32 v98, v98, v99
	ds_bpermute_b32 v99, v105, v98
	s_waitcnt lgkmcnt(0)
	v_add_f32_e32 v98, v98, v99
	ds_bpermute_b32 v99, v106, v98
	s_waitcnt lgkmcnt(0)
	v_add_f32_e32 v98, v98, v99
	ds_bpermute_b32 v99, v107, v98
	s_waitcnt lgkmcnt(0)
	v_add_f32_e32 v98, v98, v99
	v_fmamk_f32 v98, v98, 0x39800000, v108
	v_mul_f32_e32 v99, 0x4f800000, v98
	v_cmp_gt_f32_e32 vcc, s15, v98
	s_nop 1
	v_cndmask_b32_e32 v98, v98, v99, vcc
	v_sqrt_f32_e32 v99, v98
	s_nop 0
	v_add_u32_e32 v100, -1, v99
	v_add_u32_e32 v101, 1, v99
	v_fma_f32 v102, -v100, v99, v98
	v_fma_f32 v103, -v101, v99, v98
	v_cmp_ge_f32_e64 s[2:3], 0, v102
	s_nop 1
	v_cndmask_b32_e64 v99, v99, v100, s[2:3]
	v_cmp_lt_f32_e64 s[2:3], 0, v103
	s_nop 1
	v_cndmask_b32_e64 v99, v99, v101, s[2:3]
	v_mul_f32_e32 v100, 0x37800000, v99
	v_cndmask_b32_e32 v99, v99, v100, vcc
	v_cmp_class_f32_e32 vcc, v98, v109
	s_nop 1
	v_cndmask_b32_e32 v98, v99, v98, vcc
	v_div_scale_f32 v99, s[2:3], v98, v98, 1.0
	v_rcp_f32_e32 v101, v99
	v_div_scale_f32 v100, vcc, 1.0, v98, 1.0
	v_fma_f32 v102, -v99, v101, 1.0
	v_fmac_f32_e32 v101, v102, v101
	v_mul_f32_e32 v102, v100, v101
	v_fma_f32 v103, -v99, v102, v100
	v_fmac_f32_e32 v102, v103, v101
	v_fma_f32 v99, -v99, v102, v100
	v_div_fmas_f32 v99, v99, v101, v102
	v_div_fixup_f32 v98, v99, v98, 1.0
	v_pk_mul_f32 v[14:15], v[14:15], v[98:99] op_sel_hi:[1,0]
	v_pk_mul_f32 v[16:17], v[16:17], v[98:99] op_sel_hi:[1,0]
	v_pk_mul_f32 v[14:15], v[110:111], v[14:15]
	v_pk_mul_f32 v[16:17], v[112:113], v[16:17]
	v_cvt_pk_bf16_f32 v14, v14, v15
	v_pk_mul_f32 v[10:11], v[10:11], v[98:99] op_sel_hi:[1,0]
	v_cvt_pk_bf16_f32 v15, v16, v17
	global_store_dwordx2 v[96:97], v[14:15], off
	global_load_dwordx4 v[14:17], v[68:69], off offset:1024
	v_pk_mul_f32 v[12:13], v[12:13], v[98:99] op_sel_hi:[1,0]
	v_pk_mul_f32 v[6:7], v[6:7], v[98:99] op_sel_hi:[1,0]
	v_pk_mul_f32 v[8:9], v[8:9], v[98:99] op_sel_hi:[1,0]
	v_pk_mul_f32 v[2:3], v[2:3], v[98:99] op_sel_hi:[1,0]
	v_pk_mul_f32 v[4:5], v[4:5], v[98:99] op_sel_hi:[1,0]
	s_waitcnt vmcnt(0)
	v_pk_mul_f32 v[10:11], v[14:15], v[10:11]
	v_pk_mul_f32 v[12:13], v[16:17], v[12:13]
	v_cvt_pk_bf16_f32 v10, v10, v11
	s_nop 0
	v_cvt_pk_bf16_f32 v11, v12, v13
	global_store_dwordx2 v[96:97], v[10:11], off offset:512
	global_load_dwordx4 v[10:13], v[68:69], off offset:2048
	s_waitcnt vmcnt(0)
	v_pk_mul_f32 v[6:7], v[10:11], v[6:7]
	v_pk_mul_f32 v[8:9], v[12:13], v[8:9]
	v_cvt_pk_bf16_f32 v6, v6, v7
	v_pk_mul_f32 v[10:11], v[48:49], v[98:99] op_sel_hi:[1,0]
	v_cvt_pk_bf16_f32 v7, v8, v9
	global_store_dwordx2 v[96:97], v[6:7], off offset:1024
	global_load_dwordx4 v[6:9], v[68:69], off offset:3072
	s_waitcnt vmcnt(0)
	v_pk_mul_f32 v[2:3], v[2:3], v[6:7]
	v_pk_mul_f32 v[4:5], v[4:5], v[8:9]
	v_cvt_pk_bf16_f32 v2, v2, v3
	v_pk_mul_f32 v[6:7], v[62:63], v[98:99] op_sel_hi:[1,0]
	v_cvt_pk_bf16_f32 v3, v4, v5
	global_store_dwordx2 v[96:97], v[2:3], off offset:1536
	global_load_dwordx4 v[2:5], v[70:71], off
	v_pk_mul_f32 v[8:9], v[64:65], v[98:99] op_sel_hi:[1,0]
	s_waitcnt vmcnt(0)
; __device__ __forceinline__ unsigned pk2(float lo, float hi) { return pg8::cvt_pk_bf16(lo, hi); }
; template <bool OUT_BF16> __device__ __forceinline__ void rms_row(const float* xrow, const float* g, void* orow, int lane, float* ssq = nullptr) {
;     ...
;     for (int j = 0; j < 16; ++j) { const f32x4 o = v[j] * rstd * gr[64 * j];
;         if (OUT_BF16) { v2u w; w.x = pk2(o.x, o.y); w.y = pk2(o.z, o.w); ((v2u*)orow)[64 * j + lane] = w; }
;         else ((f32x4*)orow)[64 * j + lane] = o; }
; }
; __device__ __forceinline__ void prologue(const Args& a, unsigned char* lds, int vcu, int G, int wave, int lane) {
;     ...
;     for (int m = gw; m < M; m += NGW) rms_row<true>(a.in[0] + (size_t)m * DM, a.in[2], H + (size_t)m * DM, lane);
	v_pk_mul_f32 v[2:3], v[6:7], v[2:3]
	v_pk_mul_f32 v[4:5], v[8:9], v[4:5]
	v_cvt_pk_bf16_f32 v2, v2, v3
	v_pk_mul_f32 v[6:7], v[58:59], v[98:99] op_sel_hi:[1,0]
	v_cvt_pk_bf16_f32 v3, v4, v5
	global_store_dwordx2 v[96:97], v[2:3], off offset:2048
	global_load_dwordx4 v[2:5], v[72:73], off
	v_pk_mul_f32 v[8:9], v[60:61], v[98:99] op_sel_hi:[1,0]
	s_waitcnt vmcnt(0)
	v_pk_mul_f32 v[2:3], v[6:7], v[2:3]
	v_pk_mul_f32 v[4:5], v[8:9], v[4:5]
	v_cvt_pk_bf16_f32 v2, v2, v3
	v_pk_mul_f32 v[6:7], v[54:55], v[98:99] op_sel_hi:[1,0]
	v_cvt_pk_bf16_f32 v3, v4, v5
	global_store_dwordx2 v[96:97], v[2:3], off offset:2560
	global_load_dwordx4 v[2:5], v[74:75], off
	v_pk_mul_f32 v[8:9], v[56:57], v[98:99] op_sel_hi:[1,0]
	s_waitcnt vmcnt(0)
	v_pk_mul_f32 v[2:3], v[6:7], v[2:3]
	v_pk_mul_f32 v[4:5], v[8:9], v[4:5]
	v_cvt_pk_bf16_f32 v2, v2, v3
	v_pk_mul_f32 v[6:7], v[50:51], v[98:99] op_sel_hi:[1,0]
	v_cvt_pk_bf16_f32 v3, v4, v5
	global_store_dwordx2 v[96:97], v[2:3], off offset:3072
	global_load_dwordx4 v[2:5], v[76:77], off
	v_pk_mul_f32 v[8:9], v[52:53], v[98:99] op_sel_hi:[1,0]
	s_waitcnt vmcnt(0)
	v_pk_mul_f32 v[2:3], v[6:7], v[2:3]
	v_pk_mul_f32 v[4:5], v[8:9], v[4:5]
	v_cvt_pk_bf16_f32 v2, v2, v3
	v_add_co_u32_e32 v6, vcc, s12, v96
	v_cvt_pk_bf16_f32 v3, v4, v5
	global_store_dwordx2 v[96:97], v[2:3], off offset:3584
	global_load_dwordx4 v[2:5], v[78:79], off
	v_pk_mul_f32 v[8:9], v[46:47], v[98:99] op_sel_hi:[1,0]
	v_addc_co_u32_e32 v7, vcc, 0, v97, vcc
	v_lshl_add_u64 v[96:97], v[96:97], 0, s[6:7]
	s_waitcnt vmcnt(0)
	v_pk_mul_f32 v[2:3], v[8:9], v[2:3]
	v_pk_mul_f32 v[4:5], v[10:11], v[4:5]
	v_cvt_pk_bf16_f32 v2, v2, v3
	v_pk_mul_f32 v[8:9], v[42:43], v[98:99] op_sel_hi:[1,0]
	v_cvt_pk_bf16_f32 v3, v4, v5
	global_store_dwordx2 v[6:7], v[2:3], off
	global_load_dwordx4 v[2:5], v[80:81], off
	v_pk_mul_f32 v[10:11], v[44:45], v[98:99] op_sel_hi:[1,0]
	s_waitcnt vmcnt(0)
	v_pk_mul_f32 v[2:3], v[8:9], v[2:3]
	v_pk_mul_f32 v[4:5], v[10:11], v[4:5]
	v_cvt_pk_bf16_f32 v2, v2, v3
	v_pk_mul_f32 v[8:9], v[38:39], v[98:99] op_sel_hi:[1,0]
	v_cvt_pk_bf16_f32 v3, v4, v5
	global_store_dwordx2 v[6:7], v[2:3], off offset:512
	global_load_dwordx4 v[2:5], v[82:83], off
	v_pk_mul_f32 v[10:11], v[40:41], v[98:99] op_sel_hi:[1,0]
	s_waitcnt vmcnt(0)
	v_pk_mul_f32 v[2:3], v[8:9], v[2:3]
	v_pk_mul_f32 v[4:5], v[10:11], v[4:5]
	v_cvt_pk_bf16_f32 v2, v2, v3
	v_pk_mul_f32 v[8:9], v[34:35], v[98:99] op_sel_hi:[1,0]
	v_cvt_pk_bf16_f32 v3, v4, v5
	global_store_dwordx2 v[6:7], v[2:3], off offset:1024
	global_load_dwordx4 v[2:5], v[84:85], off
	v_pk_mul_f32 v[10:11], v[36:37], v[98:99] op_sel_hi:[1,0]
	s_waitcnt vmcnt(0)
	v_pk_mul_f32 v[2:3], v[8:9], v[2:3]
	v_pk_mul_f32 v[4:5], v[10:11], v[4:5]
	v_cvt_pk_bf16_f32 v2, v2, v3
	v_pk_mul_f32 v[8:9], v[30:31], v[98:99] op_sel_hi:[1,0]
	v_cvt_pk_bf16_f32 v3, v4, v5
	global_store_dwordx2 v[6:7], v[2:3], off offset:1536
	global_load_dwordx4 v[2:5], v[86:87], off
	v_pk_mul_f32 v[10:11], v[32:33], v[98:99] op_sel_hi:[1,0]
	s_waitcnt vmcnt(0)
	v_pk_mul_f32 v[2:3], v[8:9], v[2:3]
	v_pk_mul_f32 v[4:5], v[10:11], v[4:5]
	v_cvt_pk_bf16_f32 v2, v2, v3
	v_pk_mul_f32 v[8:9], v[26:27], v[98:99] op_sel_hi:[1,0]
	v_cvt_pk_bf16_f32 v3, v4, v5
	global_store_dwordx2 v[6:7], v[2:3], off offset:2048
	global_load_dwordx4 v[2:5], v[88:89], off
	v_pk_mul_f32 v[10:11], v[28:29], v[98:99] op_sel_hi:[1,0]
	s_waitcnt vmcnt(0)
	v_pk_mul_f32 v[2:3], v[8:9], v[2:3]
	v_pk_mul_f32 v[4:5], v[10:11], v[4:5]
	v_cvt_pk_bf16_f32 v2, v2, v3
	v_pk_mul_f32 v[8:9], v[22:23], v[98:99] op_sel_hi:[1,0]
	v_cvt_pk_bf16_f32 v3, v4, v5
	global_store_dwordx2 v[6:7], v[2:3], off offset:2560
	global_load_dwordx4 v[2:5], v[90:91], off
	v_pk_mul_f32 v[10:11], v[24:25], v[98:99] op_sel_hi:[1,0]
	s_waitcnt vmcnt(0)
	v_pk_mul_f32 v[2:3], v[8:9], v[2:3]
	v_pk_mul_f32 v[4:5], v[10:11], v[4:5]
	v_cvt_pk_bf16_f32 v2, v2, v3
	v_pk_mul_f32 v[8:9], v[18:19], v[98:99] op_sel_hi:[1,0]
	v_cvt_pk_bf16_f32 v3, v4, v5
	global_store_dwordx2 v[6:7], v[2:3], off offset:3072
	global_load_dwordx4 v[2:5], v[92:93], off
	v_pk_mul_f32 v[10:11], v[20:21], v[98:99] op_sel_hi:[1,0]
	s_waitcnt vmcnt(0)
	v_pk_mul_f32 v[2:3], v[8:9], v[2:3]
	v_pk_mul_f32 v[4:5], v[10:11], v[4:5]
	v_cvt_pk_bf16_f32 v2, v2, v3
	s_nop 0
	v_cvt_pk_bf16_f32 v3, v4, v5
	global_store_dwordx2 v[6:7], v[2:3], off offset:3584
	s_cbranch_scc0 .LBB0_49
